# NSA step-1 copies: rescale decision branches straight to the exps on the common path (3 taken branches + 5 SALU -> 1 branch)
# speedup vs baseline: 1.0001x; 1.0001x over previous
; DI float rowmax32(const f32x16& s0, const f32x16& s1) {
;   float a = fmaxf(fmaxf(s0[0], s0[1]), s1[0]), b = fmaxf(fmaxf(s0[2], s0[3]), s1[1]); a = fmaxf(fmaxf(a, s1[2]), s1[3]);
; #pragma unroll
;   for (int r = 4; r < 16; r += 4) { a = fmaxf(fmaxf(a, s0[r]), s0[r + 1]); b = fmaxf(fmaxf(b, s0[r + 2]), s0[r + 3]); a = fmaxf(fmaxf(a, s1[r]), s1[r + 1]); b = fmaxf(fmaxf(b, s1[r + 2]), s1[r + 3]); }
;   const float m = fmaxf(a, b);
;   return fmaxf(m, __shfl_xor(m, 32));
; }
; template <int NDVB, bool HAS_NEXT> DI void softmax_def(f32x16& sa0, f32x16& sa1, f32x16& sb0, f32x16& sb1, f32x16 (&O)[NDVB], float& muse, float& l, bool first, bf16x8 (&P)[4], bool check = true) {
;   float mx = 0.f;
;   if (check) mx = rowmax32(sa0, sa1);
;   if (check && (first || __any(mx > 8.f))) {
;     float dl = first ? mx : fmaxf(mx, 0.f);
;     if (mx < -1e29f) dl = 0.f;
;     const float alpha = __builtin_amdgcn_exp2f(-dl);
.LBB0_944:
	s_nop 6
	v_max_f32_e32 v96, v49, v49
	v_max_f32_e32 v97, v48, v48
	v_max_f32_e32 v96, v97, v96
	v_max3_f32 v97, v50, v51, v33
	v_max3_f32 v96, v96, v32, v34
	v_max3_f32 v96, v96, v35, v52
	v_max3_f32 v97, v97, v54, v55
	v_max3_f32 v96, v96, v53, v36
	v_max3_f32 v97, v97, v38, v39
	v_max3_f32 v96, v96, v37, v56
	v_max3_f32 v97, v97, v58, v59
	v_max3_f32 v96, v96, v57, v40
	v_max3_f32 v97, v97, v42, v43
	v_max3_f32 v96, v96, v41, v60
	v_max3_f32 v97, v97, v62, v63
	v_max3_f32 v96, v96, v61, v44
	v_max3_f32 v97, v97, v46, v47
	v_max3_f32 v96, v96, v45, v97
	ds_bpermute_b32 v97, v193, v96
	s_cmp_lg_u32 s89, 3
	s_waitcnt lgkmcnt(0)
	v_max_f32_e32 v97, v97, v97
	v_max_f32_e32 v96, v96, v97
	s_cbranch_scc0 .LBB0_962
	v_cmp_lt_f32_e32 vcc, s7, v96
	s_cbranch_vccz .LBB0_951
	v_max_f32_e32 v97, v96, v96
	v_max_f32_e32 v97, 0, v97
	s_branch .Lslc_resc

; template <int NDVB, bool HAS_NEXT> DI void softmax_def(f32x16& sa0, f32x16& sa1, f32x16& sb0, f32x16& sb1, f32x16 (&O)[NDVB], float& muse, float& l, bool first, bf16x8 (&P)[4], bool check = true) {
;     ...
;     float dl = first ? mx : fmaxf(mx, 0.f);
;     if (mx < -1e29f) dl = 0.f;
;     const float alpha = __builtin_amdgcn_exp2f(-dl);
;     muse += dl; l *= alpha;
; #pragma unroll
;     for (int i = 0; i < 16; ++i) { sa0[i] -= dl; sa1[i] -= dl; }
;     if (HAS_NEXT) {
; #pragma unroll
;       for (int i = 0; i < 16; ++i) { sb0[i] -= dl; sb1[i] -= dl; }
;     }
; #pragma unroll
;     for (int d = 0; d < NDVB; ++d)
; #pragma unroll
;       for (int i = 0; i < 16; ++i) O[d][i] *= alpha;
;   }
.Lslc_resc:
	v_cmp_ngt_f32_e32 vcc, s1, v96
	s_nop 1
	v_cndmask_b32_e32 v96, 0, v97, vcc
	v_exp_f32_e64 v98, -v96
	v_add_f32_e32 v138, v138, v96
	v_pk_add_f32 v[48:49], v[48:49], v[96:97] op_sel_hi:[1,0] neg_lo:[0,1] neg_hi:[0,1]
	v_pk_add_f32 v[32:33], v[32:33], v[96:97] op_sel_hi:[1,0] neg_lo:[0,1] neg_hi:[0,1]
	v_mul_f32_e32 v219, v219, v98
	v_pk_add_f32 v[50:51], v[50:51], v[96:97] op_sel_hi:[1,0] neg_lo:[0,1] neg_hi:[0,1]
	v_pk_add_f32 v[34:35], v[34:35], v[96:97] op_sel_hi:[1,0] neg_lo:[0,1] neg_hi:[0,1]
	v_pk_add_f32 v[52:53], v[52:53], v[96:97] op_sel_hi:[1,0] neg_lo:[0,1] neg_hi:[0,1]
	v_pk_add_f32 v[36:37], v[36:37], v[96:97] op_sel_hi:[1,0] neg_lo:[0,1] neg_hi:[0,1]
	v_pk_add_f32 v[54:55], v[54:55], v[96:97] op_sel_hi:[1,0] neg_lo:[0,1] neg_hi:[0,1]
	v_pk_add_f32 v[38:39], v[38:39], v[96:97] op_sel_hi:[1,0] neg_lo:[0,1] neg_hi:[0,1]
	v_pk_add_f32 v[56:57], v[56:57], v[96:97] op_sel_hi:[1,0] neg_lo:[0,1] neg_hi:[0,1]
	v_pk_add_f32 v[40:41], v[40:41], v[96:97] op_sel_hi:[1,0] neg_lo:[0,1] neg_hi:[0,1]
	v_pk_add_f32 v[58:59], v[58:59], v[96:97] op_sel_hi:[1,0] neg_lo:[0,1] neg_hi:[0,1]
	v_pk_add_f32 v[42:43], v[42:43], v[96:97] op_sel_hi:[1,0] neg_lo:[0,1] neg_hi:[0,1]
	v_pk_add_f32 v[60:61], v[60:61], v[96:97] op_sel_hi:[1,0] neg_lo:[0,1] neg_hi:[0,1]
	v_pk_add_f32 v[44:45], v[44:45], v[96:97] op_sel_hi:[1,0] neg_lo:[0,1] neg_hi:[0,1]
	v_pk_add_f32 v[62:63], v[62:63], v[96:97] op_sel_hi:[1,0] neg_lo:[0,1] neg_hi:[0,1]
	v_pk_add_f32 v[46:47], v[46:47], v[96:97] op_sel_hi:[1,0] neg_lo:[0,1] neg_hi:[0,1]
	v_pk_mul_f32 v[30:31], v[30:31], v[98:99] op_sel_hi:[1,0]
	v_pk_mul_f32 v[28:29], v[28:29], v[98:99] op_sel_hi:[1,0]
	v_pk_mul_f32 v[26:27], v[26:27], v[98:99] op_sel_hi:[1,0]
	v_pk_mul_f32 v[24:25], v[24:25], v[98:99] op_sel_hi:[1,0]
	v_pk_mul_f32 v[22:23], v[22:23], v[98:99] op_sel_hi:[1,0]
	v_pk_mul_f32 v[20:21], v[20:21], v[98:99] op_sel_hi:[1,0]
	v_pk_mul_f32 v[18:19], v[18:19], v[98:99] op_sel_hi:[1,0]
	v_pk_mul_f32 v[16:17], v[16:17], v[98:99] op_sel_hi:[1,0]
	v_pk_mul_f32 v[14:15], v[14:15], v[98:99] op_sel_hi:[1,0]
	v_pk_mul_f32 v[12:13], v[12:13], v[98:99] op_sel_hi:[1,0]
	v_pk_mul_f32 v[10:11], v[10:11], v[98:99] op_sel_hi:[1,0]
	v_pk_mul_f32 v[8:9], v[8:9], v[98:99] op_sel_hi:[1,0]
	v_pk_mul_f32 v[6:7], v[6:7], v[98:99] op_sel_hi:[1,0]
	v_pk_mul_f32 v[4:5], v[4:5], v[98:99] op_sel_hi:[1,0]
	v_pk_mul_f32 v[2:3], v[2:3], v[98:99] op_sel_hi:[1,0]
	v_pk_mul_f32 v[0:1], v[0:1], v[98:99] op_sel_hi:[1,0]

; DI float rowmax32(const f32x16& s0, const f32x16& s1) {
;   float a = fmaxf(fmaxf(s0[0], s0[1]), s1[0]), b = fmaxf(fmaxf(s0[2], s0[3]), s1[1]); a = fmaxf(fmaxf(a, s1[2]), s1[3]);
; #pragma unroll
;   for (int r = 4; r < 16; r += 4) { a = fmaxf(fmaxf(a, s0[r]), s0[r + 1]); b = fmaxf(fmaxf(b, s0[r + 2]), s0[r + 3]); a = fmaxf(fmaxf(a, s1[r]), s1[r + 1]); b = fmaxf(fmaxf(b, s1[r + 2]), s1[r + 3]); }
;   const float m = fmaxf(a, b);
;   return fmaxf(m, __shfl_xor(m, 32));
; }
; template <int NDVB, bool HAS_NEXT> DI void softmax_def(f32x16& sa0, f32x16& sa1, f32x16& sb0, f32x16& sb1, f32x16 (&O)[NDVB], float& muse, float& l, bool first, bf16x8 (&P)[4], bool check = true) {
;   float mx = 0.f;
;   if (check) mx = rowmax32(sa0, sa1);
;   if (check && (first || __any(mx > 8.f))) {
;     float dl = first ? mx : fmaxf(mx, 0.f);
;     if (mx < -1e29f) dl = 0.f;
;     const float alpha = __builtin_amdgcn_exp2f(-dl);
.LBB0_987:
	v_max_f32_e32 v129, v113, v113
	v_max_f32_e32 v130, v112, v112
	v_max_f32_e32 v129, v130, v129
	v_max3_f32 v130, v114, v115, v97
	v_max3_f32 v129, v129, v96, v98
	v_max3_f32 v129, v129, v99, v116
	v_max3_f32 v130, v130, v118, v119
	v_max3_f32 v129, v129, v117, v100
	v_max3_f32 v130, v130, v102, v103
	v_max3_f32 v129, v129, v101, v120
	v_max3_f32 v130, v130, v122, v123
	v_max3_f32 v129, v129, v121, v104
	v_max3_f32 v130, v130, v106, v107
	v_max3_f32 v129, v129, v105, v124
	v_max3_f32 v130, v130, v126, v127
	v_max3_f32 v129, v129, v125, v108
	v_max3_f32 v130, v130, v110, v111
	v_max3_f32 v129, v129, v109, v130
	ds_bpermute_b32 v130, v193, v129
	s_cmp_lg_u32 s46, 3
	s_waitcnt lgkmcnt(0)
	v_max_f32_e32 v130, v130, v130
	v_max_f32_e32 v129, v129, v130
	s_cbranch_scc0 .LBB0_1005
	v_cmp_lt_f32_e32 vcc, s7, v129
	s_cbranch_vccz .LBB0_994
	v_max_f32_e32 v130, v129, v129
	v_max_f32_e32 v130, 0, v130
	s_branch .Lwin_resc

; template <int NDVB, bool HAS_NEXT> DI void softmax_def(f32x16& sa0, f32x16& sa1, f32x16& sb0, f32x16& sb1, f32x16 (&O)[NDVB], float& muse, float& l, bool first, bf16x8 (&P)[4], bool check = true) {
;     ...
;     float dl = first ? mx : fmaxf(mx, 0.f);
;     if (mx < -1e29f) dl = 0.f;
;     const float alpha = __builtin_amdgcn_exp2f(-dl);
;     muse += dl; l *= alpha;
; #pragma unroll
;     for (int i = 0; i < 16; ++i) { sa0[i] -= dl; sa1[i] -= dl; }
;     if (HAS_NEXT) {
; #pragma unroll
;       for (int i = 0; i < 16; ++i) { sb0[i] -= dl; sb1[i] -= dl; }
;     }
; #pragma unroll
;     for (int d = 0; d < NDVB; ++d)
; #pragma unroll
;       for (int i = 0; i < 16; ++i) O[d][i] *= alpha;
;   }
.Lwin_resc:
	v_cmp_ngt_f32_e32 vcc, s85, v129
	s_nop 1
	v_cndmask_b32_e32 v130, 0, v130, vcc
	v_exp_f32_e64 v132, -v130
	v_add_f32_e32 v221, v221, v130
	v_pk_add_f32 v[112:113], v[112:113], v[130:131] op_sel_hi:[1,0] neg_lo:[0,1] neg_hi:[0,1]
	v_pk_add_f32 v[96:97], v[96:97], v[130:131] op_sel_hi:[1,0] neg_lo:[0,1] neg_hi:[0,1]
	v_mul_f32_e32 v128, v128, v132
	v_pk_add_f32 v[114:115], v[114:115], v[130:131] op_sel_hi:[1,0] neg_lo:[0,1] neg_hi:[0,1]
	v_pk_add_f32 v[98:99], v[98:99], v[130:131] op_sel_hi:[1,0] neg_lo:[0,1] neg_hi:[0,1]
	v_pk_add_f32 v[116:117], v[116:117], v[130:131] op_sel_hi:[1,0] neg_lo:[0,1] neg_hi:[0,1]
	v_pk_add_f32 v[100:101], v[100:101], v[130:131] op_sel_hi:[1,0] neg_lo:[0,1] neg_hi:[0,1]
	v_pk_add_f32 v[118:119], v[118:119], v[130:131] op_sel_hi:[1,0] neg_lo:[0,1] neg_hi:[0,1]
	v_pk_add_f32 v[102:103], v[102:103], v[130:131] op_sel_hi:[1,0] neg_lo:[0,1] neg_hi:[0,1]
	v_pk_add_f32 v[120:121], v[120:121], v[130:131] op_sel_hi:[1,0] neg_lo:[0,1] neg_hi:[0,1]
	v_pk_add_f32 v[104:105], v[104:105], v[130:131] op_sel_hi:[1,0] neg_lo:[0,1] neg_hi:[0,1]
	v_pk_add_f32 v[122:123], v[122:123], v[130:131] op_sel_hi:[1,0] neg_lo:[0,1] neg_hi:[0,1]
	v_pk_add_f32 v[106:107], v[106:107], v[130:131] op_sel_hi:[1,0] neg_lo:[0,1] neg_hi:[0,1]
	v_pk_add_f32 v[124:125], v[124:125], v[130:131] op_sel_hi:[1,0] neg_lo:[0,1] neg_hi:[0,1]
	v_pk_add_f32 v[108:109], v[108:109], v[130:131] op_sel_hi:[1,0] neg_lo:[0,1] neg_hi:[0,1]
	v_pk_add_f32 v[126:127], v[126:127], v[130:131] op_sel_hi:[1,0] neg_lo:[0,1] neg_hi:[0,1]
	v_pk_add_f32 v[110:111], v[110:111], v[130:131] op_sel_hi:[1,0] neg_lo:[0,1] neg_hi:[0,1]
	v_pk_mul_f32 v[62:63], v[62:63], v[132:133] op_sel_hi:[1,0]
	v_pk_mul_f32 v[60:61], v[60:61], v[132:133] op_sel_hi:[1,0]
	v_pk_mul_f32 v[58:59], v[58:59], v[132:133] op_sel_hi:[1,0]
	v_pk_mul_f32 v[56:57], v[56:57], v[132:133] op_sel_hi:[1,0]
	v_pk_mul_f32 v[54:55], v[54:55], v[132:133] op_sel_hi:[1,0]
	v_pk_mul_f32 v[52:53], v[52:53], v[132:133] op_sel_hi:[1,0]
	v_pk_mul_f32 v[50:51], v[50:51], v[132:133] op_sel_hi:[1,0]
	v_pk_mul_f32 v[48:49], v[48:49], v[132:133] op_sel_hi:[1,0]
	v_pk_mul_f32 v[46:47], v[46:47], v[132:133] op_sel_hi:[1,0]
	v_pk_mul_f32 v[44:45], v[44:45], v[132:133] op_sel_hi:[1,0]
	v_pk_mul_f32 v[42:43], v[42:43], v[132:133] op_sel_hi:[1,0]
	v_pk_mul_f32 v[40:41], v[40:41], v[132:133] op_sel_hi:[1,0]
	v_pk_mul_f32 v[38:39], v[38:39], v[132:133] op_sel_hi:[1,0]
	v_pk_mul_f32 v[36:37], v[36:37], v[132:133] op_sel_hi:[1,0]
	v_pk_mul_f32 v[34:35], v[34:35], v[132:133] op_sel_hi:[1,0]
	v_pk_mul_f32 v[32:33], v[32:33], v[132:133] op_sel_hi:[1,0]
